# L1 in-proj epilogue: the cos/sin table loads of rope blocks 1-7 issued at the start of each block (before its norm/reduce/divide) instead of right before their vmcnt(0); same registers, predicate reco
# speedup vs baseline: 1.0037x; 1.0037x over previous
.LBB0_185:
	v_lshl_add_u32 v195, s47, 8, v188
	v_lshl_or_b32 v162, s48, 8, v192
	s_cmp_lt_i32 s48, 8
	s_mov_b64 s[4:5], -1
	s_cbranch_scc0 .LBB0_204
	s_cmp_lt_i32 s48, 4
	s_cselect_b64 vcc, -1, 0
	s_and_b64 s[4:5], vcc, exec
	s_cselect_b32 s5, s17, s19
	s_cselect_b32 s4, s16, s18
	global_load_dwordx4 v[130:133], v194, s[4:5] offset:16
	global_load_dwordx4 v[134:137], v194, s[4:5]
	v_mov_b32_e32 v0, 0x3e38aa3b
	v_cndmask_b32_e32 v0, 1.0, v0, vcc
	s_cmpk_lt_i32 s47, 0x80
	s_cselect_b64 s[6:7], -1, 0
	s_cmpk_gt_i32 s47, 0x7f
	s_waitcnt vmcnt(0)
	v_pk_mul_f32 v[176:177], v[0:1], v[132:133] op_sel_hi:[0,1]
	v_pk_mul_f32 v[168:169], v[0:1], v[136:137] op_sel_hi:[0,1]
	v_pk_mul_f32 v[170:171], v[0:1], v[134:135] op_sel_hi:[0,1]
	global_load_dwordx4 v[134:137], v194, s[4:5] offset:144
	global_load_dwordx4 v[164:167], v194, s[4:5] offset:128
	v_pk_mul_f32 v[178:179], v[0:1], v[130:131] op_sel_hi:[0,1]
	v_pk_mul_f32 v[130:131], v[128:129], v[128:129]
	v_pk_mul_f32 v[132:133], v[126:127], v[126:127]
	s_waitcnt vmcnt(0)
	s_cbranch_scc1 .Lrh_0
	v_lshlrev_b32_e32 v234, 7, v195
	v_and_b32_e32 v234, 0x3e780, v234
	v_mov_b32_e32 v235, 0
	v_lshl_add_u64 v[236:237], v[146:147], 0, v[234:235]
	global_load_dwordx4 v[196:199], v[236:237], off offset:16
	global_load_dwordx4 v[200:203], v[236:237], off
	v_lshl_add_u64 v[236:237], v[156:157], 0, v[234:235]
	global_load_dwordx4 v[204:207], v[236:237], off offset:16
	global_load_dwordx4 v[208:211], v[236:237], off
.Lrh_0:
	v_pk_mul_f32 v[172:173], v[0:1], v[166:167] op_sel_hi:[0,1]
	v_pk_mul_f32 v[166:167], v[0:1], v[134:135] op_sel_hi:[0,1]
	v_pk_mov_b32 v[134:135], v[132:133], v[130:131] op_sel:[1,0]
	v_mov_b32_e32 v133, v131
	v_pk_add_f32 v[130:131], v[134:135], v[132:133]
	v_pk_mul_f32 v[132:133], v[124:125], v[124:125]
	v_pk_mul_f32 v[134:135], v[122:123], v[122:123]
	v_pk_mul_f32 v[174:175], v[0:1], v[164:165] op_sel_hi:[0,1]
	v_pk_mul_f32 v[164:165], v[0:1], v[136:137] op_sel_hi:[0,1]
	v_pk_mov_b32 v[136:137], v[134:135], v[132:133] op_sel:[1,0]
	v_mov_b32_e32 v135, v133
	v_pk_add_f32 v[132:133], v[136:137], v[134:135]
	v_mul_f32_e32 v0, v106, v106
	v_mul_f32_e32 v134, v107, v107
	v_pk_add_f32 v[130:131], v[130:131], v[130:131] op_sel:[0,1] op_sel_hi:[1,0]
	v_pk_add_f32 v[132:133], v[132:133], v[132:133] op_sel:[0,1] op_sel_hi:[1,0]
	v_mov_b32_e32 v131, v0
	v_mov_b32_e32 v133, v134
	v_mul_f32_e32 v0, v111, v111
	v_mul_f32_e32 v135, v108, v108
	v_pk_add_f32 v[130:131], v[130:131], v[132:133]
	v_pk_fma_f32 v[132:133], v[110:111], v[110:111], v[0:1] op_sel_hi:[1,1,0]
	v_mul_f32_e32 v0, v113, v113
	v_mul_f32_e32 v136, v109, v109
	v_mov_b32_e32 v133, v135
	v_pk_fma_f32 v[134:135], v[112:113], v[112:113], v[0:1] op_sel_hi:[1,1,0]
	s_nop 0
	v_mov_b32_e32 v135, v136
	v_pk_add_f32 v[132:133], v[132:133], v[134:135]
	s_nop 0
	v_pk_add_f32 v[130:131], v[130:131], v[132:133]
	s_nop 0
	v_add_f32_e32 v0, v130, v131
	ds_bpermute_b32 v130, v190, v0
	s_waitcnt lgkmcnt(0)
	v_add_f32_e32 v0, v0, v130
	ds_bpermute_b32 v130, v191, v0
	s_waitcnt lgkmcnt(0)
	v_add_f32_e32 v0, v0, v130
	v_fmamk_f32 v0, v0, 0x3c800000, v240
	v_cmp_gt_f32_e32 vcc, s77, v0
	v_mul_f32_e32 v130, 0x4f800000, v0
	s_nop 0
	v_cndmask_b32_e32 v0, v0, v130, vcc
	v_sqrt_f32_e32 v130, v0
	s_nop 0
	v_add_u32_e32 v131, -1, v130
	v_fma_f32 v132, -v131, v130, v0
	v_cmp_ge_f32_e64 s[4:5], 0, v132
	v_add_u32_e32 v132, 1, v130
	s_nop 0
	v_cndmask_b32_e64 v131, v130, v131, s[4:5]
	v_fma_f32 v130, -v132, v130, v0
	v_cmp_lt_f32_e64 s[4:5], 0, v130
	s_nop 1
	v_cndmask_b32_e64 v130, v131, v132, s[4:5]
	v_mul_f32_e32 v131, 0x37800000, v130
	v_cndmask_b32_e32 v130, v130, v131, vcc
	v_cmp_class_f32_e32 vcc, v0, v241
	s_nop 1
	v_cndmask_b32_e32 v0, v130, v0, vcc
	v_div_scale_f32 v130, s[4:5], v0, v0, 1.0
	v_rcp_f32_e32 v131, v130
	s_nop 0
	v_fma_f32 v132, -v130, v131, 1.0
	v_fmac_f32_e32 v131, v132, v131
	v_div_scale_f32 v132, vcc, 1.0, v0, 1.0
	v_mul_f32_e32 v133, v132, v131
	v_fma_f32 v134, -v130, v133, v132
	v_fmac_f32_e32 v133, v134, v131
	v_fma_f32 v130, -v130, v133, v132
	v_div_fmas_f32 v130, v130, v131, v133
	v_div_fixup_f32 v0, v130, v0, 1.0
	v_pk_mul_f32 v[130:131], v[126:127], v[0:1] op_sel_hi:[1,0]
	v_pk_mul_f32 v[132:133], v[128:129], v[0:1] op_sel_hi:[1,0]
	v_pk_mul_f32 v[148:149], v[110:111], v[0:1] op_sel_hi:[1,0]
	v_pk_mul_f32 v[150:151], v[112:113], v[0:1] op_sel_hi:[1,0]
	v_pk_mul_f32 v[136:137], v[168:169], v[132:133]
	v_pk_mul_f32 v[134:135], v[170:171], v[130:131]
	v_pk_mul_f32 v[130:131], v[122:123], v[0:1] op_sel_hi:[1,0]
	v_pk_mul_f32 v[132:133], v[124:125], v[0:1] op_sel_hi:[1,0]
	v_pk_mul_f32 v[180:181], v[172:173], v[150:151]
	v_pk_mul_f32 v[182:183], v[174:175], v[148:149]
	v_pk_mul_f32 v[148:149], v[106:107], v[0:1] op_sel_hi:[1,0]
	v_pk_mul_f32 v[150:151], v[108:109], v[0:1] op_sel_hi:[1,0]
	v_pk_mul_f32 v[132:133], v[176:177], v[132:133]
	v_pk_mul_f32 v[130:131], v[178:179], v[130:131]
	v_pk_mul_f32 v[184:185], v[164:165], v[150:151]
	v_pk_mul_f32 v[186:187], v[166:167], v[148:149]
	s_cbranch_scc1 .LBB0_188
	s_waitcnt vmcnt(0)
	v_pk_mul_f32 v[150:151], v[182:183], v[208:209]
	v_pk_mul_f32 v[148:149], v[180:181], v[210:211]
	v_pk_fma_f32 v[212:213], v[134:135], v[200:201], v[150:151] neg_lo:[0,0,1] neg_hi:[0,0,1]
	v_pk_mul_f32 v[134:135], v[134:135], v[208:209]
	v_pk_fma_f32 v[214:215], v[136:137], v[202:203], v[148:149] neg_lo:[0,0,1] neg_hi:[0,0,1]
	v_pk_mul_f32 v[136:137], v[136:137], v[210:211]
	v_pk_fma_f32 v[182:183], v[182:183], v[200:201], v[134:135]
	v_pk_mul_f32 v[134:135], v[184:185], v[206:207]
	v_pk_mul_f32 v[148:149], v[186:187], v[204:205]
	v_pk_fma_f32 v[180:181], v[180:181], v[202:203], v[136:137]
	v_pk_fma_f32 v[136:137], v[132:133], v[198:199], v[134:135] neg_lo:[0,0,1] neg_hi:[0,0,1]
	v_pk_fma_f32 v[134:135], v[130:131], v[196:197], v[148:149] neg_lo:[0,0,1] neg_hi:[0,0,1]
	v_pk_mul_f32 v[132:133], v[132:133], v[206:207]
	v_pk_mul_f32 v[130:131], v[130:131], v[204:205]
	v_pk_fma_f32 v[184:185], v[184:185], v[198:199], v[132:133]
	v_pk_fma_f32 v[186:187], v[186:187], v[196:197], v[130:131]
	v_mov_b64_e32 v[130:131], v[134:135]
	v_mov_b64_e32 v[132:133], v[136:137]
	v_mov_b64_e32 v[134:135], v[212:213]
	v_mov_b64_e32 v[136:137], v[214:215]
.LBB0_188:
	v_mov_b64_e32 v[148:149], s[60:61]
	v_ashrrev_i32_e32 v163, 31, v162
	v_mad_i64_i32 v[148:149], s[4:5], v195, s30, v[148:149]
	v_lshl_add_u64 v[148:149], v[162:163], 1, v[148:149]
	v_cvt_pk_bf16_f32 v134, v134, v135
	v_cvt_pk_bf16_f32 v135, v136, v137
	v_cvt_pk_bf16_f32 v136, v130, v131
	v_cvt_pk_bf16_f32 v137, v132, v133
	v_cvt_pk_bf16_f32 v130, v182, v183
	v_cvt_pk_bf16_f32 v131, v180, v181
	v_cvt_pk_bf16_f32 v132, v186, v187
	v_cvt_pk_bf16_f32 v133, v184, v185
	global_store_dwordx4 v[148:149], v[134:137], off
	global_store_dwordx4 v[148:149], v[130:133], off offset:64
	v_mul_f32_e32 v0, v90, v90
	v_or_b32_e32 v196, 16, v195
	s_cmpk_gt_i32 s47, 0x7f
	s_cbranch_scc1 .Lrh_1
	v_lshlrev_b32_e32 v234, 7, v196
	v_and_b32_e32 v234, 0x3ef80, v234
	v_mov_b32_e32 v235, 0
	v_lshl_add_u64 v[236:237], v[146:147], 0, v[234:235]
	global_load_dwordx4 v[198:201], v[236:237], off offset:16
	global_load_dwordx4 v[202:205], v[236:237], off
	v_lshl_add_u64 v[236:237], v[156:157], 0, v[234:235]
	global_load_dwordx4 v[206:209], v[236:237], off offset:16
	global_load_dwordx4 v[210:213], v[236:237], off
.Lrh_1:
	v_pk_mul_f32 v[130:131], v[120:121], v[120:121]
	v_pk_mul_f32 v[132:133], v[118:119], v[118:119]
	s_nop 0
	v_pk_mov_b32 v[134:135], v[132:133], v[130:131] op_sel:[1,0]
	v_mov_b32_e32 v133, v131
	v_pk_add_f32 v[130:131], v[134:135], v[132:133]
	v_pk_mul_f32 v[132:133], v[116:117], v[116:117]
	v_pk_mul_f32 v[134:135], v[114:115], v[114:115]
	v_pk_add_f32 v[130:131], v[130:131], v[130:131] op_sel:[0,1] op_sel_hi:[1,0]
	v_pk_mov_b32 v[136:137], v[134:135], v[132:133] op_sel:[1,0]
	v_mov_b32_e32 v135, v133
	v_pk_add_f32 v[132:133], v[136:137], v[134:135]
	v_mul_f32_e32 v134, v91, v91
	v_pk_add_f32 v[132:133], v[132:133], v[132:133] op_sel:[0,1] op_sel_hi:[1,0]
	v_mov_b32_e32 v131, v0
	v_mov_b32_e32 v133, v134
	v_mul_f32_e32 v0, v95, v95
	v_mul_f32_e32 v135, v92, v92
	v_pk_add_f32 v[130:131], v[130:131], v[132:133]
	v_pk_fma_f32 v[132:133], v[94:95], v[94:95], v[0:1] op_sel_hi:[1,1,0]
	v_mul_f32_e32 v0, v97, v97
	v_mul_f32_e32 v136, v93, v93
	v_mov_b32_e32 v133, v135
	v_pk_fma_f32 v[134:135], v[96:97], v[96:97], v[0:1] op_sel_hi:[1,1,0]
	s_nop 0
	v_mov_b32_e32 v135, v136
	v_pk_add_f32 v[132:133], v[132:133], v[134:135]
	s_nop 0
	v_pk_add_f32 v[130:131], v[130:131], v[132:133]
	s_nop 0
	v_add_f32_e32 v0, v130, v131
	ds_bpermute_b32 v130, v190, v0
	s_waitcnt lgkmcnt(0)
	v_add_f32_e32 v0, v0, v130
	ds_bpermute_b32 v130, v191, v0
	s_waitcnt lgkmcnt(0)
	v_add_f32_e32 v0, v0, v130
	v_fmamk_f32 v0, v0, 0x3c800000, v240
	v_cmp_gt_f32_e32 vcc, s77, v0
	v_mul_f32_e32 v130, 0x4f800000, v0
	s_nop 0
	v_cndmask_b32_e32 v0, v0, v130, vcc
	v_sqrt_f32_e32 v130, v0
	s_nop 0
	v_add_u32_e32 v131, -1, v130
	v_fma_f32 v132, -v131, v130, v0
	v_cmp_ge_f32_e64 s[4:5], 0, v132
	v_add_u32_e32 v132, 1, v130
	s_nop 0
	v_cndmask_b32_e64 v131, v130, v131, s[4:5]
	v_fma_f32 v130, -v132, v130, v0
	v_cmp_lt_f32_e64 s[4:5], 0, v130
	s_nop 1
	v_cndmask_b32_e64 v130, v131, v132, s[4:5]
	v_mul_f32_e32 v131, 0x37800000, v130
	v_cndmask_b32_e32 v130, v130, v131, vcc
	v_cmp_class_f32_e32 vcc, v0, v241
	s_nop 1
	v_cndmask_b32_e32 v0, v130, v0, vcc
	v_div_scale_f32 v130, s[4:5], v0, v0, 1.0
	v_rcp_f32_e32 v131, v130
	s_nop 0
	v_fma_f32 v132, -v130, v131, 1.0
	v_fmac_f32_e32 v131, v132, v131
	v_div_scale_f32 v132, vcc, 1.0, v0, 1.0
	v_mul_f32_e32 v133, v132, v131
	v_fma_f32 v134, -v130, v133, v132
	v_fmac_f32_e32 v133, v134, v131
	v_fma_f32 v130, -v130, v133, v132
	v_div_fmas_f32 v130, v130, v131, v133
	v_div_fixup_f32 v0, v130, v0, 1.0
	v_pk_mul_f32 v[130:131], v[118:119], v[0:1] op_sel_hi:[1,0]
	v_pk_mul_f32 v[132:133], v[120:121], v[0:1] op_sel_hi:[1,0]
	v_pk_mul_f32 v[148:149], v[94:95], v[0:1] op_sel_hi:[1,0]
	v_pk_mul_f32 v[150:151], v[96:97], v[0:1] op_sel_hi:[1,0]
	v_pk_mul_f32 v[136:137], v[168:169], v[132:133]
	v_pk_mul_f32 v[134:135], v[170:171], v[130:131]
	v_pk_mul_f32 v[130:131], v[114:115], v[0:1] op_sel_hi:[1,0]
	v_pk_mul_f32 v[132:133], v[116:117], v[0:1] op_sel_hi:[1,0]
	v_pk_mul_f32 v[180:181], v[172:173], v[150:151]
	v_pk_mul_f32 v[182:183], v[174:175], v[148:149]
	v_pk_mul_f32 v[148:149], v[90:91], v[0:1] op_sel_hi:[1,0]
	v_pk_mul_f32 v[150:151], v[92:93], v[0:1] op_sel_hi:[1,0]
	v_cndmask_b32_e64 v0, 0, 1, s[6:7]
	v_pk_mul_f32 v[132:133], v[176:177], v[132:133]
	v_pk_mul_f32 v[130:131], v[178:179], v[130:131]
	v_pk_mul_f32 v[184:185], v[164:165], v[150:151]
	v_pk_mul_f32 v[186:187], v[166:167], v[148:149]
	v_cmp_ne_u32_e64 s[4:5], 1, v0
	s_andn2_b64 vcc, exec, s[6:7]
	s_cbranch_vccnz .LBB0_190
	s_waitcnt vmcnt(0)
	v_pk_mul_f32 v[150:151], v[182:183], v[210:211]
	v_pk_mul_f32 v[148:149], v[180:181], v[212:213]
	v_pk_fma_f32 v[214:215], v[134:135], v[202:203], v[150:151] neg_lo:[0,0,1] neg_hi:[0,0,1]
	v_pk_mul_f32 v[134:135], v[134:135], v[210:211]
	v_pk_fma_f32 v[216:217], v[136:137], v[204:205], v[148:149] neg_lo:[0,0,1] neg_hi:[0,0,1]
	v_pk_mul_f32 v[136:137], v[136:137], v[212:213]
	v_pk_fma_f32 v[182:183], v[182:183], v[202:203], v[134:135]
	v_pk_mul_f32 v[134:135], v[184:185], v[208:209]
	v_pk_mul_f32 v[148:149], v[186:187], v[206:207]
	v_pk_fma_f32 v[180:181], v[180:181], v[204:205], v[136:137]
	v_pk_fma_f32 v[136:137], v[132:133], v[200:201], v[134:135] neg_lo:[0,0,1] neg_hi:[0,0,1]
	v_pk_fma_f32 v[134:135], v[130:131], v[198:199], v[148:149] neg_lo:[0,0,1] neg_hi:[0,0,1]
	v_pk_mul_f32 v[132:133], v[132:133], v[208:209]
	v_pk_mul_f32 v[130:131], v[130:131], v[206:207]
	v_pk_fma_f32 v[184:185], v[184:185], v[200:201], v[132:133]
	v_pk_fma_f32 v[186:187], v[186:187], v[198:199], v[130:131]
	v_mov_b64_e32 v[130:131], v[134:135]
	v_mov_b64_e32 v[132:133], v[136:137]
	v_mov_b64_e32 v[134:135], v[214:215]
	v_mov_b64_e32 v[136:137], v[216:217]
.LBB0_190:
	v_mov_b64_e32 v[148:149], s[60:61]
	v_mad_i64_i32 v[148:149], s[6:7], v196, s30, v[148:149]
	v_lshl_add_u64 v[148:149], v[162:163], 1, v[148:149]
	v_cvt_pk_bf16_f32 v134, v134, v135
	v_cvt_pk_bf16_f32 v135, v136, v137
	v_cvt_pk_bf16_f32 v136, v130, v131
	v_cvt_pk_bf16_f32 v137, v132, v133
	v_cvt_pk_bf16_f32 v130, v182, v183
	v_cvt_pk_bf16_f32 v131, v180, v181
	v_cvt_pk_bf16_f32 v132, v186, v187
	v_cvt_pk_bf16_f32 v133, v184, v185
	global_store_dwordx4 v[148:149], v[134:137], off
	global_store_dwordx4 v[148:149], v[130:133], off offset:64
	v_mul_f32_e32 v0, v74, v74
	v_or_b32_e32 v196, 32, v195
	s_cmpk_gt_i32 s47, 0x7f
	s_cbranch_scc1 .Lrh_2
	v_lshlrev_b32_e32 v234, 7, v196
	v_and_b32_e32 v234, 0x3f780, v234
	v_mov_b32_e32 v235, 0
	v_lshl_add_u64 v[236:237], v[146:147], 0, v[234:235]
	global_load_dwordx4 v[198:201], v[236:237], off offset:16
	global_load_dwordx4 v[202:205], v[236:237], off
	v_lshl_add_u64 v[236:237], v[156:157], 0, v[234:235]
	global_load_dwordx4 v[206:209], v[236:237], off offset:16
	global_load_dwordx4 v[210:213], v[236:237], off
.Lrh_2:
	v_pk_mul_f32 v[130:131], v[104:105], v[104:105]
	v_pk_mul_f32 v[132:133], v[102:103], v[102:103]
	s_nop 0
	v_pk_mov_b32 v[134:135], v[132:133], v[130:131] op_sel:[1,0]
	v_mov_b32_e32 v133, v131
	v_pk_add_f32 v[130:131], v[134:135], v[132:133]
	v_pk_mul_f32 v[132:133], v[100:101], v[100:101]
	v_pk_mul_f32 v[134:135], v[98:99], v[98:99]
	v_pk_add_f32 v[130:131], v[130:131], v[130:131] op_sel:[0,1] op_sel_hi:[1,0]
	v_pk_mov_b32 v[136:137], v[134:135], v[132:133] op_sel:[1,0]
	v_mov_b32_e32 v135, v133
	v_pk_add_f32 v[132:133], v[136:137], v[134:135]
	v_mul_f32_e32 v134, v75, v75
	v_pk_add_f32 v[132:133], v[132:133], v[132:133] op_sel:[0,1] op_sel_hi:[1,0]
	v_mov_b32_e32 v131, v0
	v_mov_b32_e32 v133, v134
	v_mul_f32_e32 v0, v79, v79
	v_mul_f32_e32 v135, v76, v76
	v_pk_add_f32 v[130:131], v[130:131], v[132:133]
	v_pk_fma_f32 v[132:133], v[78:79], v[78:79], v[0:1] op_sel_hi:[1,1,0]
	v_mul_f32_e32 v0, v81, v81
	v_mul_f32_e32 v136, v77, v77
	v_mov_b32_e32 v133, v135
	v_pk_fma_f32 v[134:135], v[80:81], v[80:81], v[0:1] op_sel_hi:[1,1,0]
	s_nop 0
	v_mov_b32_e32 v135, v136
	v_pk_add_f32 v[132:133], v[132:133], v[134:135]
	s_nop 0
	v_pk_add_f32 v[130:131], v[130:131], v[132:133]
	s_nop 0
	v_add_f32_e32 v0, v130, v131
	ds_bpermute_b32 v130, v190, v0
	s_waitcnt lgkmcnt(0)
	v_add_f32_e32 v0, v0, v130
	ds_bpermute_b32 v130, v191, v0
	s_waitcnt lgkmcnt(0)
	v_add_f32_e32 v0, v0, v130
	v_fmamk_f32 v0, v0, 0x3c800000, v240
	v_cmp_gt_f32_e32 vcc, s77, v0
	v_mul_f32_e32 v130, 0x4f800000, v0
	s_nop 0
	v_cndmask_b32_e32 v0, v0, v130, vcc
	v_sqrt_f32_e32 v130, v0
	s_nop 0
	v_add_u32_e32 v131, -1, v130
	v_fma_f32 v132, -v131, v130, v0
	v_cmp_ge_f32_e64 s[6:7], 0, v132
	v_add_u32_e32 v132, 1, v130
	s_nop 0
	v_cndmask_b32_e64 v131, v130, v131, s[6:7]
	v_fma_f32 v130, -v132, v130, v0
	v_cmp_lt_f32_e64 s[6:7], 0, v130
	s_nop 1
	v_cndmask_b32_e64 v130, v131, v132, s[6:7]
	v_mul_f32_e32 v131, 0x37800000, v130
	v_cndmask_b32_e32 v130, v130, v131, vcc
	v_cmp_class_f32_e32 vcc, v0, v241
	s_nop 1
	v_cndmask_b32_e32 v0, v130, v0, vcc
	v_div_scale_f32 v130, s[6:7], v0, v0, 1.0
	v_rcp_f32_e32 v131, v130
	s_nop 0
	v_fma_f32 v132, -v130, v131, 1.0
	v_fmac_f32_e32 v131, v132, v131
	v_div_scale_f32 v132, vcc, 1.0, v0, 1.0
	v_mul_f32_e32 v133, v132, v131
	v_fma_f32 v134, -v130, v133, v132
	v_fmac_f32_e32 v133, v134, v131
	v_fma_f32 v130, -v130, v133, v132
	v_div_fmas_f32 v130, v130, v131, v133
	v_div_fixup_f32 v0, v130, v0, 1.0
	v_pk_mul_f32 v[130:131], v[102:103], v[0:1] op_sel_hi:[1,0]
	v_pk_mul_f32 v[132:133], v[104:105], v[0:1] op_sel_hi:[1,0]
	v_pk_mul_f32 v[148:149], v[78:79], v[0:1] op_sel_hi:[1,0]
	v_pk_mul_f32 v[150:151], v[80:81], v[0:1] op_sel_hi:[1,0]
	v_pk_mul_f32 v[136:137], v[168:169], v[132:133]
	v_pk_mul_f32 v[134:135], v[170:171], v[130:131]
	v_pk_mul_f32 v[130:131], v[98:99], v[0:1] op_sel_hi:[1,0]
	v_pk_mul_f32 v[132:133], v[100:101], v[0:1] op_sel_hi:[1,0]
	v_pk_mul_f32 v[180:181], v[172:173], v[150:151]
	v_pk_mul_f32 v[182:183], v[174:175], v[148:149]
	v_pk_mul_f32 v[148:149], v[74:75], v[0:1] op_sel_hi:[1,0]
	v_pk_mul_f32 v[150:151], v[76:77], v[0:1] op_sel_hi:[1,0]
	v_pk_mul_f32 v[132:133], v[176:177], v[132:133]
	v_pk_mul_f32 v[130:131], v[178:179], v[130:131]
	v_pk_mul_f32 v[184:185], v[164:165], v[150:151]
	v_pk_mul_f32 v[186:187], v[166:167], v[148:149]
	s_and_b64 vcc, exec, s[4:5]
	s_cbranch_vccnz .LBB0_192
	s_waitcnt vmcnt(0)
	v_pk_mul_f32 v[150:151], v[182:183], v[210:211]
	v_pk_mul_f32 v[148:149], v[180:181], v[212:213]
	v_pk_fma_f32 v[214:215], v[134:135], v[202:203], v[150:151] neg_lo:[0,0,1] neg_hi:[0,0,1]
	v_pk_mul_f32 v[134:135], v[134:135], v[210:211]
	v_pk_fma_f32 v[216:217], v[136:137], v[204:205], v[148:149] neg_lo:[0,0,1] neg_hi:[0,0,1]
	v_pk_mul_f32 v[136:137], v[136:137], v[212:213]
	v_pk_fma_f32 v[182:183], v[182:183], v[202:203], v[134:135]
	v_pk_mul_f32 v[134:135], v[184:185], v[208:209]
	v_pk_mul_f32 v[148:149], v[186:187], v[206:207]
	v_pk_fma_f32 v[180:181], v[180:181], v[204:205], v[136:137]
	v_pk_fma_f32 v[136:137], v[132:133], v[200:201], v[134:135] neg_lo:[0,0,1] neg_hi:[0,0,1]
	v_pk_fma_f32 v[134:135], v[130:131], v[198:199], v[148:149] neg_lo:[0,0,1] neg_hi:[0,0,1]
	v_pk_mul_f32 v[132:133], v[132:133], v[208:209]
	v_pk_mul_f32 v[130:131], v[130:131], v[206:207]
	v_pk_fma_f32 v[184:185], v[184:185], v[200:201], v[132:133]
	v_pk_fma_f32 v[186:187], v[186:187], v[198:199], v[130:131]
	v_mov_b64_e32 v[130:131], v[134:135]
	v_mov_b64_e32 v[132:133], v[136:137]
	v_mov_b64_e32 v[134:135], v[214:215]
	v_mov_b64_e32 v[136:137], v[216:217]
.LBB0_192:
	v_mov_b64_e32 v[148:149], s[60:61]
	v_mad_i64_i32 v[148:149], s[6:7], v196, s30, v[148:149]
	v_lshl_add_u64 v[148:149], v[162:163], 1, v[148:149]
	v_cvt_pk_bf16_f32 v134, v134, v135
	v_cvt_pk_bf16_f32 v135, v136, v137
	v_cvt_pk_bf16_f32 v136, v130, v131
	v_cvt_pk_bf16_f32 v137, v132, v133
	v_cvt_pk_bf16_f32 v130, v182, v183
	v_cvt_pk_bf16_f32 v131, v180, v181
	v_cvt_pk_bf16_f32 v132, v186, v187
	v_cvt_pk_bf16_f32 v133, v184, v185
	global_store_dwordx4 v[148:149], v[134:137], off
	global_store_dwordx4 v[148:149], v[130:133], off offset:64
	v_mul_f32_e32 v0, v66, v66
	v_or_b32_e32 v196, 48, v195
	s_cmpk_gt_i32 s47, 0x7f
	s_cbranch_scc1 .Lrh_3
	v_lshlrev_b32_e32 v234, 7, v196
	v_and_b32_e32 v234, 0x3ff80, v234
	v_mov_b32_e32 v235, 0
	v_lshl_add_u64 v[236:237], v[146:147], 0, v[234:235]
	global_load_dwordx4 v[198:201], v[236:237], off offset:16
	global_load_dwordx4 v[202:205], v[236:237], off
	v_lshl_add_u64 v[236:237], v[156:157], 0, v[234:235]
	global_load_dwordx4 v[206:209], v[236:237], off offset:16
	global_load_dwordx4 v[210:213], v[236:237], off
.Lrh_3:
	v_pk_mul_f32 v[130:131], v[88:89], v[88:89]
	v_pk_mul_f32 v[132:133], v[86:87], v[86:87]
	s_nop 0
	v_pk_mov_b32 v[134:135], v[132:133], v[130:131] op_sel:[1,0]
	v_mov_b32_e32 v133, v131
	v_pk_add_f32 v[130:131], v[134:135], v[132:133]
	v_pk_mul_f32 v[132:133], v[84:85], v[84:85]
	v_pk_mul_f32 v[134:135], v[82:83], v[82:83]
	v_pk_add_f32 v[130:131], v[130:131], v[130:131] op_sel:[0,1] op_sel_hi:[1,0]
	v_pk_mov_b32 v[136:137], v[134:135], v[132:133] op_sel:[1,0]
	v_mov_b32_e32 v135, v133
	v_pk_add_f32 v[132:133], v[136:137], v[134:135]
	v_mul_f32_e32 v134, v67, v67
	v_pk_add_f32 v[132:133], v[132:133], v[132:133] op_sel:[0,1] op_sel_hi:[1,0]
	v_mov_b32_e32 v131, v0
	v_mov_b32_e32 v133, v134
	v_mul_f32_e32 v0, v71, v71
	v_mul_f32_e32 v135, v68, v68
	v_pk_add_f32 v[130:131], v[130:131], v[132:133]
	v_pk_fma_f32 v[132:133], v[70:71], v[70:71], v[0:1] op_sel_hi:[1,1,0]
	v_mul_f32_e32 v0, v73, v73
	v_mul_f32_e32 v136, v69, v69
	v_mov_b32_e32 v133, v135
	v_pk_fma_f32 v[134:135], v[72:73], v[72:73], v[0:1] op_sel_hi:[1,1,0]
	s_nop 0
	v_mov_b32_e32 v135, v136
	v_pk_add_f32 v[132:133], v[132:133], v[134:135]
	s_nop 0
	v_pk_add_f32 v[130:131], v[130:131], v[132:133]
	s_nop 0
	v_add_f32_e32 v0, v130, v131
	ds_bpermute_b32 v130, v190, v0
	s_waitcnt lgkmcnt(0)
	v_add_f32_e32 v0, v0, v130
	ds_bpermute_b32 v130, v191, v0
	s_waitcnt lgkmcnt(0)
	v_add_f32_e32 v0, v0, v130
	v_fmamk_f32 v0, v0, 0x3c800000, v240
	v_cmp_gt_f32_e32 vcc, s77, v0
	v_mul_f32_e32 v130, 0x4f800000, v0
	s_nop 0
	v_cndmask_b32_e32 v0, v0, v130, vcc
	v_sqrt_f32_e32 v130, v0
	s_nop 0
	v_add_u32_e32 v131, -1, v130
	v_fma_f32 v132, -v131, v130, v0
	v_cmp_ge_f32_e64 s[6:7], 0, v132
	v_add_u32_e32 v132, 1, v130
	s_nop 0
	v_cndmask_b32_e64 v131, v130, v131, s[6:7]
	v_fma_f32 v130, -v132, v130, v0
	v_cmp_lt_f32_e64 s[6:7], 0, v130
	s_nop 1
	v_cndmask_b32_e64 v130, v131, v132, s[6:7]
	v_mul_f32_e32 v131, 0x37800000, v130
	v_cndmask_b32_e32 v130, v130, v131, vcc
	v_cmp_class_f32_e32 vcc, v0, v241
	s_nop 1
	v_cndmask_b32_e32 v0, v130, v0, vcc
	v_div_scale_f32 v130, s[6:7], v0, v0, 1.0
	v_rcp_f32_e32 v131, v130
	s_nop 0
	v_fma_f32 v132, -v130, v131, 1.0
	v_fmac_f32_e32 v131, v132, v131
	v_div_scale_f32 v132, vcc, 1.0, v0, 1.0
	v_mul_f32_e32 v133, v132, v131
	v_fma_f32 v134, -v130, v133, v132
	v_fmac_f32_e32 v133, v134, v131
	v_fma_f32 v130, -v130, v133, v132
	v_div_fmas_f32 v130, v130, v131, v133
	v_div_fixup_f32 v0, v130, v0, 1.0
	v_pk_mul_f32 v[130:131], v[86:87], v[0:1] op_sel_hi:[1,0]
	v_pk_mul_f32 v[132:133], v[88:89], v[0:1] op_sel_hi:[1,0]
	v_pk_mul_f32 v[148:149], v[70:71], v[0:1] op_sel_hi:[1,0]
	v_pk_mul_f32 v[150:151], v[72:73], v[0:1] op_sel_hi:[1,0]
	v_pk_mul_f32 v[136:137], v[168:169], v[132:133]
	v_pk_mul_f32 v[134:135], v[170:171], v[130:131]
	v_pk_mul_f32 v[130:131], v[82:83], v[0:1] op_sel_hi:[1,0]
	v_pk_mul_f32 v[132:133], v[84:85], v[0:1] op_sel_hi:[1,0]
	v_pk_mul_f32 v[180:181], v[172:173], v[150:151]
	v_pk_mul_f32 v[182:183], v[174:175], v[148:149]
	v_pk_mul_f32 v[148:149], v[66:67], v[0:1] op_sel_hi:[1,0]
	v_pk_mul_f32 v[150:151], v[68:69], v[0:1] op_sel_hi:[1,0]
	v_pk_mul_f32 v[132:133], v[176:177], v[132:133]
	v_pk_mul_f32 v[130:131], v[178:179], v[130:131]
	v_pk_mul_f32 v[184:185], v[164:165], v[150:151]
	v_pk_mul_f32 v[186:187], v[166:167], v[148:149]
	s_and_b64 vcc, exec, s[4:5]
	s_cbranch_vccnz .LBB0_194
	s_waitcnt vmcnt(0)
	v_pk_mul_f32 v[150:151], v[182:183], v[210:211]
	v_pk_mul_f32 v[148:149], v[180:181], v[212:213]
	v_pk_fma_f32 v[214:215], v[134:135], v[202:203], v[150:151] neg_lo:[0,0,1] neg_hi:[0,0,1]
	v_pk_mul_f32 v[134:135], v[134:135], v[210:211]
	v_pk_fma_f32 v[216:217], v[136:137], v[204:205], v[148:149] neg_lo:[0,0,1] neg_hi:[0,0,1]
	v_pk_mul_f32 v[136:137], v[136:137], v[212:213]
	v_pk_fma_f32 v[182:183], v[182:183], v[202:203], v[134:135]
	v_pk_mul_f32 v[134:135], v[184:185], v[208:209]
	v_pk_mul_f32 v[148:149], v[186:187], v[206:207]
	v_pk_fma_f32 v[180:181], v[180:181], v[204:205], v[136:137]
	v_pk_fma_f32 v[136:137], v[132:133], v[200:201], v[134:135] neg_lo:[0,0,1] neg_hi:[0,0,1]
	v_pk_fma_f32 v[134:135], v[130:131], v[198:199], v[148:149] neg_lo:[0,0,1] neg_hi:[0,0,1]
	v_pk_mul_f32 v[132:133], v[132:133], v[208:209]
	v_pk_mul_f32 v[130:131], v[130:131], v[206:207]
	v_pk_fma_f32 v[184:185], v[184:185], v[200:201], v[132:133]
	v_pk_fma_f32 v[186:187], v[186:187], v[198:199], v[130:131]
	v_mov_b64_e32 v[130:131], v[134:135]
	v_mov_b64_e32 v[132:133], v[136:137]
	v_mov_b64_e32 v[134:135], v[214:215]
	v_mov_b64_e32 v[136:137], v[216:217]
.LBB0_194:
	v_mov_b64_e32 v[148:149], s[60:61]
	v_mad_i64_i32 v[148:149], s[6:7], v196, s30, v[148:149]
	v_lshl_add_u64 v[148:149], v[162:163], 1, v[148:149]
	v_cvt_pk_bf16_f32 v134, v134, v135
	v_cvt_pk_bf16_f32 v135, v136, v137
	v_cvt_pk_bf16_f32 v136, v130, v131
	v_cvt_pk_bf16_f32 v137, v132, v133
	v_cvt_pk_bf16_f32 v130, v182, v183
	v_cvt_pk_bf16_f32 v131, v180, v181
	v_cvt_pk_bf16_f32 v132, v186, v187
	v_cvt_pk_bf16_f32 v133, v184, v185
	global_store_dwordx4 v[148:149], v[134:137], off
	global_store_dwordx4 v[148:149], v[130:133], off offset:64
	v_mul_f32_e32 v0, v42, v42
	v_add_u32_e32 v196, 0x80, v195
	s_cmpk_gt_i32 s47, 0x7f
	s_cbranch_scc1 .Lrh_4
	v_lshlrev_b32_e32 v234, 7, v196
	v_and_b32_e32 v234, 0x3e780, v234
	v_mov_b32_e32 v235, 0
	v_lshl_add_u64 v[236:237], v[146:147], 0, v[234:235]
	global_load_dwordx4 v[198:201], v[236:237], off offset:16
	global_load_dwordx4 v[202:205], v[236:237], off
	v_lshl_add_u64 v[236:237], v[156:157], 0, v[234:235]
	global_load_dwordx4 v[206:209], v[236:237], off offset:16
	global_load_dwordx4 v[210:213], v[236:237], off
.Lrh_4:
	v_pk_mul_f32 v[130:131], v[64:65], v[64:65]
	v_pk_mul_f32 v[132:133], v[62:63], v[62:63]
	s_nop 0
	v_pk_mov_b32 v[134:135], v[132:133], v[130:131] op_sel:[1,0]
	v_mov_b32_e32 v133, v131
	v_pk_add_f32 v[130:131], v[134:135], v[132:133]
	v_pk_mul_f32 v[132:133], v[60:61], v[60:61]
	v_pk_mul_f32 v[134:135], v[58:59], v[58:59]
	v_pk_add_f32 v[130:131], v[130:131], v[130:131] op_sel:[0,1] op_sel_hi:[1,0]
	v_pk_mov_b32 v[136:137], v[134:135], v[132:133] op_sel:[1,0]
	v_mov_b32_e32 v135, v133
	v_pk_add_f32 v[132:133], v[136:137], v[134:135]
	v_mul_f32_e32 v134, v43, v43
	v_pk_add_f32 v[132:133], v[132:133], v[132:133] op_sel:[0,1] op_sel_hi:[1,0]
	v_mov_b32_e32 v131, v0
	v_mov_b32_e32 v133, v134
	v_mul_f32_e32 v0, v47, v47
	v_mul_f32_e32 v135, v44, v44
	v_pk_add_f32 v[130:131], v[130:131], v[132:133]
	v_pk_fma_f32 v[132:133], v[46:47], v[46:47], v[0:1] op_sel_hi:[1,1,0]
	v_mul_f32_e32 v0, v49, v49
	v_mul_f32_e32 v136, v45, v45
	v_mov_b32_e32 v133, v135
	v_pk_fma_f32 v[134:135], v[48:49], v[48:49], v[0:1] op_sel_hi:[1,1,0]
	s_nop 0
	v_mov_b32_e32 v135, v136
	v_pk_add_f32 v[132:133], v[132:133], v[134:135]
	s_nop 0
	v_pk_add_f32 v[130:131], v[130:131], v[132:133]
	s_nop 0
	v_add_f32_e32 v0, v130, v131
	ds_bpermute_b32 v130, v190, v0
	s_waitcnt lgkmcnt(0)
	v_add_f32_e32 v0, v0, v130
	ds_bpermute_b32 v130, v191, v0
	s_waitcnt lgkmcnt(0)
	v_add_f32_e32 v0, v0, v130
	v_fmamk_f32 v0, v0, 0x3c800000, v240
	v_cmp_gt_f32_e32 vcc, s77, v0
	v_mul_f32_e32 v130, 0x4f800000, v0
	s_nop 0
	v_cndmask_b32_e32 v0, v0, v130, vcc
	v_sqrt_f32_e32 v130, v0
	s_nop 0
	v_add_u32_e32 v131, -1, v130
	v_fma_f32 v132, -v131, v130, v0
	v_cmp_ge_f32_e64 s[6:7], 0, v132
	v_add_u32_e32 v132, 1, v130
	s_nop 0
	v_cndmask_b32_e64 v131, v130, v131, s[6:7]
	v_fma_f32 v130, -v132, v130, v0
	v_cmp_lt_f32_e64 s[6:7], 0, v130
	s_nop 1
	v_cndmask_b32_e64 v130, v131, v132, s[6:7]
	v_mul_f32_e32 v131, 0x37800000, v130
	v_cndmask_b32_e32 v130, v130, v131, vcc
	v_cmp_class_f32_e32 vcc, v0, v241
	s_nop 1
	v_cndmask_b32_e32 v0, v130, v0, vcc
	v_div_scale_f32 v130, s[6:7], v0, v0, 1.0
	v_rcp_f32_e32 v131, v130
	s_nop 0
	v_fma_f32 v132, -v130, v131, 1.0
	v_fmac_f32_e32 v131, v132, v131
	v_div_scale_f32 v132, vcc, 1.0, v0, 1.0
	v_mul_f32_e32 v133, v132, v131
	v_fma_f32 v134, -v130, v133, v132
	v_fmac_f32_e32 v133, v134, v131
	v_fma_f32 v130, -v130, v133, v132
	v_div_fmas_f32 v130, v130, v131, v133
	v_div_fixup_f32 v0, v130, v0, 1.0
	v_pk_mul_f32 v[130:131], v[62:63], v[0:1] op_sel_hi:[1,0]
	v_pk_mul_f32 v[132:133], v[64:65], v[0:1] op_sel_hi:[1,0]
	v_pk_mul_f32 v[148:149], v[46:47], v[0:1] op_sel_hi:[1,0]
	v_pk_mul_f32 v[150:151], v[48:49], v[0:1] op_sel_hi:[1,0]
	v_pk_mul_f32 v[136:137], v[168:169], v[132:133]
	v_pk_mul_f32 v[134:135], v[170:171], v[130:131]
	v_pk_mul_f32 v[130:131], v[58:59], v[0:1] op_sel_hi:[1,0]
	v_pk_mul_f32 v[132:133], v[60:61], v[0:1] op_sel_hi:[1,0]
	v_pk_mul_f32 v[180:181], v[172:173], v[150:151]
	v_pk_mul_f32 v[182:183], v[174:175], v[148:149]
	v_pk_mul_f32 v[148:149], v[42:43], v[0:1] op_sel_hi:[1,0]
	v_pk_mul_f32 v[150:151], v[44:45], v[0:1] op_sel_hi:[1,0]
	v_pk_mul_f32 v[132:133], v[176:177], v[132:133]
	v_pk_mul_f32 v[130:131], v[178:179], v[130:131]
	v_pk_mul_f32 v[184:185], v[164:165], v[150:151]
	v_pk_mul_f32 v[186:187], v[166:167], v[148:149]
	s_and_b64 vcc, exec, s[4:5]
	s_cbranch_vccnz .LBB0_196
	s_waitcnt vmcnt(0)
	v_pk_mul_f32 v[150:151], v[182:183], v[210:211]
	v_pk_mul_f32 v[148:149], v[180:181], v[212:213]
	v_pk_fma_f32 v[214:215], v[134:135], v[202:203], v[150:151] neg_lo:[0,0,1] neg_hi:[0,0,1]
	v_pk_mul_f32 v[134:135], v[134:135], v[210:211]
	v_pk_fma_f32 v[216:217], v[136:137], v[204:205], v[148:149] neg_lo:[0,0,1] neg_hi:[0,0,1]
	v_pk_mul_f32 v[136:137], v[136:137], v[212:213]
	v_pk_fma_f32 v[182:183], v[182:183], v[202:203], v[134:135]
	v_pk_mul_f32 v[134:135], v[184:185], v[208:209]
	v_pk_mul_f32 v[148:149], v[186:187], v[206:207]
	v_pk_fma_f32 v[180:181], v[180:181], v[204:205], v[136:137]
	v_pk_fma_f32 v[136:137], v[132:133], v[200:201], v[134:135] neg_lo:[0,0,1] neg_hi:[0,0,1]
	v_pk_fma_f32 v[134:135], v[130:131], v[198:199], v[148:149] neg_lo:[0,0,1] neg_hi:[0,0,1]
	v_pk_mul_f32 v[132:133], v[132:133], v[208:209]
	v_pk_mul_f32 v[130:131], v[130:131], v[206:207]
	v_pk_fma_f32 v[184:185], v[184:185], v[200:201], v[132:133]
	v_pk_fma_f32 v[186:187], v[186:187], v[198:199], v[130:131]
	v_mov_b64_e32 v[130:131], v[134:135]
	v_mov_b64_e32 v[132:133], v[136:137]
	v_mov_b64_e32 v[134:135], v[214:215]
	v_mov_b64_e32 v[136:137], v[216:217]
.LBB0_196:
	v_mov_b64_e32 v[148:149], s[60:61]
	v_mad_i64_i32 v[148:149], s[6:7], v196, s30, v[148:149]
	v_lshl_add_u64 v[148:149], v[162:163], 1, v[148:149]
	v_cvt_pk_bf16_f32 v134, v134, v135
	v_cvt_pk_bf16_f32 v135, v136, v137
	v_cvt_pk_bf16_f32 v136, v130, v131
	v_cvt_pk_bf16_f32 v137, v132, v133
	v_cvt_pk_bf16_f32 v130, v182, v183
	v_cvt_pk_bf16_f32 v131, v180, v181
	v_cvt_pk_bf16_f32 v132, v186, v187
	v_cvt_pk_bf16_f32 v133, v184, v185
	global_store_dwordx4 v[148:149], v[134:137], off
	global_store_dwordx4 v[148:149], v[130:133], off offset:64
	v_mul_f32_e32 v0, v26, v26
	v_add_u32_e32 v196, 0x90, v195
	s_cmpk_gt_i32 s47, 0x7f
	s_cbranch_scc1 .Lrh_5
	v_lshlrev_b32_e32 v234, 7, v196
	v_and_b32_e32 v234, 0x3ef80, v234
	v_mov_b32_e32 v235, 0
	v_lshl_add_u64 v[236:237], v[146:147], 0, v[234:235]
	global_load_dwordx4 v[198:201], v[236:237], off offset:16
	global_load_dwordx4 v[202:205], v[236:237], off
	v_lshl_add_u64 v[236:237], v[156:157], 0, v[234:235]
	global_load_dwordx4 v[206:209], v[236:237], off offset:16
	global_load_dwordx4 v[210:213], v[236:237], off
.Lrh_5:
	v_pk_mul_f32 v[130:131], v[56:57], v[56:57]
	v_pk_mul_f32 v[132:133], v[54:55], v[54:55]
	s_nop 0
	v_pk_mov_b32 v[134:135], v[132:133], v[130:131] op_sel:[1,0]
	v_mov_b32_e32 v133, v131
	v_pk_add_f32 v[130:131], v[134:135], v[132:133]
	v_pk_mul_f32 v[132:133], v[52:53], v[52:53]
	v_pk_mul_f32 v[134:135], v[50:51], v[50:51]
	v_pk_add_f32 v[130:131], v[130:131], v[130:131] op_sel:[0,1] op_sel_hi:[1,0]
	v_pk_mov_b32 v[136:137], v[134:135], v[132:133] op_sel:[1,0]
	v_mov_b32_e32 v135, v133
	v_pk_add_f32 v[132:133], v[136:137], v[134:135]
	v_mul_f32_e32 v134, v27, v27
	v_pk_add_f32 v[132:133], v[132:133], v[132:133] op_sel:[0,1] op_sel_hi:[1,0]
	v_mov_b32_e32 v131, v0
	v_mov_b32_e32 v133, v134
	v_mul_f32_e32 v0, v31, v31
	v_mul_f32_e32 v135, v28, v28
	v_pk_add_f32 v[130:131], v[130:131], v[132:133]
	v_pk_fma_f32 v[132:133], v[30:31], v[30:31], v[0:1] op_sel_hi:[1,1,0]
	v_mul_f32_e32 v0, v33, v33
	v_mul_f32_e32 v136, v29, v29
	v_mov_b32_e32 v133, v135
	v_pk_fma_f32 v[134:135], v[32:33], v[32:33], v[0:1] op_sel_hi:[1,1,0]
	s_nop 0
	v_mov_b32_e32 v135, v136
	v_pk_add_f32 v[132:133], v[132:133], v[134:135]
	s_nop 0
	v_pk_add_f32 v[130:131], v[130:131], v[132:133]
	s_nop 0
	v_add_f32_e32 v0, v130, v131
	ds_bpermute_b32 v130, v190, v0
	s_waitcnt lgkmcnt(0)
	v_add_f32_e32 v0, v0, v130
	ds_bpermute_b32 v130, v191, v0
	s_waitcnt lgkmcnt(0)
	v_add_f32_e32 v0, v0, v130
	v_fmamk_f32 v0, v0, 0x3c800000, v240
	v_cmp_gt_f32_e32 vcc, s77, v0
	v_mul_f32_e32 v130, 0x4f800000, v0
	s_nop 0
	v_cndmask_b32_e32 v0, v0, v130, vcc
	v_sqrt_f32_e32 v130, v0
	s_nop 0
	v_add_u32_e32 v131, -1, v130
	v_fma_f32 v132, -v131, v130, v0
	v_cmp_ge_f32_e64 s[6:7], 0, v132
	v_add_u32_e32 v132, 1, v130
	s_nop 0
	v_cndmask_b32_e64 v131, v130, v131, s[6:7]
	v_fma_f32 v130, -v132, v130, v0
	v_cmp_lt_f32_e64 s[6:7], 0, v130
	s_nop 1
	v_cndmask_b32_e64 v130, v131, v132, s[6:7]
	v_mul_f32_e32 v131, 0x37800000, v130
	v_cndmask_b32_e32 v130, v130, v131, vcc
	v_cmp_class_f32_e32 vcc, v0, v241
	s_nop 1
	v_cndmask_b32_e32 v0, v130, v0, vcc
	v_div_scale_f32 v130, s[6:7], v0, v0, 1.0
	v_rcp_f32_e32 v131, v130
	s_nop 0
	v_fma_f32 v132, -v130, v131, 1.0
	v_fmac_f32_e32 v131, v132, v131
	v_div_scale_f32 v132, vcc, 1.0, v0, 1.0
	v_mul_f32_e32 v133, v132, v131
	v_fma_f32 v134, -v130, v133, v132
	v_fmac_f32_e32 v133, v134, v131
	v_fma_f32 v130, -v130, v133, v132
	v_div_fmas_f32 v130, v130, v131, v133
	v_div_fixup_f32 v0, v130, v0, 1.0
	v_pk_mul_f32 v[130:131], v[54:55], v[0:1] op_sel_hi:[1,0]
	v_pk_mul_f32 v[132:133], v[56:57], v[0:1] op_sel_hi:[1,0]
	v_pk_mul_f32 v[148:149], v[30:31], v[0:1] op_sel_hi:[1,0]
	v_pk_mul_f32 v[150:151], v[32:33], v[0:1] op_sel_hi:[1,0]
	v_pk_mul_f32 v[136:137], v[168:169], v[132:133]
	v_pk_mul_f32 v[134:135], v[170:171], v[130:131]
	v_pk_mul_f32 v[130:131], v[50:51], v[0:1] op_sel_hi:[1,0]
	v_pk_mul_f32 v[132:133], v[52:53], v[0:1] op_sel_hi:[1,0]
	v_pk_mul_f32 v[180:181], v[172:173], v[150:151]
	v_pk_mul_f32 v[182:183], v[174:175], v[148:149]
	v_pk_mul_f32 v[148:149], v[26:27], v[0:1] op_sel_hi:[1,0]
	v_pk_mul_f32 v[150:151], v[28:29], v[0:1] op_sel_hi:[1,0]
	v_pk_mul_f32 v[132:133], v[176:177], v[132:133]
	v_pk_mul_f32 v[130:131], v[178:179], v[130:131]
	v_pk_mul_f32 v[184:185], v[164:165], v[150:151]
	v_pk_mul_f32 v[186:187], v[166:167], v[148:149]
	s_and_b64 vcc, exec, s[4:5]
	s_cbranch_vccnz .LBB0_198
	s_waitcnt vmcnt(0)
	v_pk_mul_f32 v[150:151], v[182:183], v[210:211]
	v_pk_mul_f32 v[148:149], v[180:181], v[212:213]
	v_pk_fma_f32 v[214:215], v[134:135], v[202:203], v[150:151] neg_lo:[0,0,1] neg_hi:[0,0,1]
	v_pk_mul_f32 v[134:135], v[134:135], v[210:211]
	v_pk_fma_f32 v[216:217], v[136:137], v[204:205], v[148:149] neg_lo:[0,0,1] neg_hi:[0,0,1]
	v_pk_mul_f32 v[136:137], v[136:137], v[212:213]
	v_pk_fma_f32 v[182:183], v[182:183], v[202:203], v[134:135]
	v_pk_mul_f32 v[134:135], v[184:185], v[208:209]
	v_pk_mul_f32 v[148:149], v[186:187], v[206:207]
	v_pk_fma_f32 v[180:181], v[180:181], v[204:205], v[136:137]
	v_pk_fma_f32 v[136:137], v[132:133], v[200:201], v[134:135] neg_lo:[0,0,1] neg_hi:[0,0,1]
	v_pk_fma_f32 v[134:135], v[130:131], v[198:199], v[148:149] neg_lo:[0,0,1] neg_hi:[0,0,1]
	v_pk_mul_f32 v[132:133], v[132:133], v[208:209]
	v_pk_mul_f32 v[130:131], v[130:131], v[206:207]
	v_pk_fma_f32 v[184:185], v[184:185], v[200:201], v[132:133]
	v_pk_fma_f32 v[186:187], v[186:187], v[198:199], v[130:131]
	v_mov_b64_e32 v[130:131], v[134:135]
	v_mov_b64_e32 v[132:133], v[136:137]
	v_mov_b64_e32 v[134:135], v[214:215]
	v_mov_b64_e32 v[136:137], v[216:217]
.LBB0_198:
	v_mov_b64_e32 v[148:149], s[60:61]
	v_mad_i64_i32 v[148:149], s[6:7], v196, s30, v[148:149]
	v_lshl_add_u64 v[148:149], v[162:163], 1, v[148:149]
	v_cvt_pk_bf16_f32 v134, v134, v135
	v_cvt_pk_bf16_f32 v135, v136, v137
	v_cvt_pk_bf16_f32 v136, v130, v131
	v_cvt_pk_bf16_f32 v137, v132, v133
	v_cvt_pk_bf16_f32 v130, v182, v183
	v_cvt_pk_bf16_f32 v131, v180, v181
	v_cvt_pk_bf16_f32 v132, v186, v187
	v_cvt_pk_bf16_f32 v133, v184, v185
	global_store_dwordx4 v[148:149], v[134:137], off
	global_store_dwordx4 v[148:149], v[130:133], off offset:64
	v_mul_f32_e32 v0, v10, v10
	v_add_u32_e32 v196, 0xa0, v195
	s_cmpk_gt_i32 s47, 0x7f
	s_cbranch_scc1 .Lrh_6
	v_lshlrev_b32_e32 v234, 7, v196
	v_and_b32_e32 v234, 0x3f780, v234
	v_mov_b32_e32 v235, 0
	v_lshl_add_u64 v[236:237], v[146:147], 0, v[234:235]
	global_load_dwordx4 v[198:201], v[236:237], off offset:16
	global_load_dwordx4 v[202:205], v[236:237], off
	v_lshl_add_u64 v[236:237], v[156:157], 0, v[234:235]
	global_load_dwordx4 v[206:209], v[236:237], off offset:16
	global_load_dwordx4 v[210:213], v[236:237], off
.Lrh_6:
	v_pk_mul_f32 v[130:131], v[40:41], v[40:41]
	v_pk_mul_f32 v[132:133], v[38:39], v[38:39]
	s_nop 0
	v_pk_mov_b32 v[134:135], v[132:133], v[130:131] op_sel:[1,0]
	v_mov_b32_e32 v133, v131
	v_pk_add_f32 v[130:131], v[134:135], v[132:133]
	v_pk_mul_f32 v[132:133], v[36:37], v[36:37]
	v_pk_mul_f32 v[134:135], v[34:35], v[34:35]
	v_pk_add_f32 v[130:131], v[130:131], v[130:131] op_sel:[0,1] op_sel_hi:[1,0]
	v_pk_mov_b32 v[136:137], v[134:135], v[132:133] op_sel:[1,0]
	v_mov_b32_e32 v135, v133
	v_pk_add_f32 v[132:133], v[136:137], v[134:135]
	v_mul_f32_e32 v134, v11, v11
	v_pk_add_f32 v[132:133], v[132:133], v[132:133] op_sel:[0,1] op_sel_hi:[1,0]
	v_mov_b32_e32 v131, v0
	v_mov_b32_e32 v133, v134
	v_mul_f32_e32 v0, v15, v15
	v_mul_f32_e32 v135, v12, v12
	v_pk_add_f32 v[130:131], v[130:131], v[132:133]
	v_pk_fma_f32 v[132:133], v[14:15], v[14:15], v[0:1] op_sel_hi:[1,1,0]
	v_mul_f32_e32 v0, v17, v17
	v_mul_f32_e32 v136, v13, v13
	v_mov_b32_e32 v133, v135
	v_pk_fma_f32 v[134:135], v[16:17], v[16:17], v[0:1] op_sel_hi:[1,1,0]
	s_nop 0
	v_mov_b32_e32 v135, v136
	v_pk_add_f32 v[132:133], v[132:133], v[134:135]
	s_nop 0
	v_pk_add_f32 v[130:131], v[130:131], v[132:133]
	s_nop 0
	v_add_f32_e32 v0, v130, v131
	ds_bpermute_b32 v130, v190, v0
	s_waitcnt lgkmcnt(0)
	v_add_f32_e32 v0, v0, v130
	ds_bpermute_b32 v130, v191, v0
	s_waitcnt lgkmcnt(0)
	v_add_f32_e32 v0, v0, v130
	v_fmamk_f32 v0, v0, 0x3c800000, v240
	v_cmp_gt_f32_e32 vcc, s77, v0
	v_mul_f32_e32 v130, 0x4f800000, v0
	s_nop 0
	v_cndmask_b32_e32 v0, v0, v130, vcc
	v_sqrt_f32_e32 v130, v0
	s_nop 0
	v_add_u32_e32 v131, -1, v130
	v_fma_f32 v132, -v131, v130, v0
	v_cmp_ge_f32_e64 s[6:7], 0, v132
	v_add_u32_e32 v132, 1, v130
	s_nop 0
	v_cndmask_b32_e64 v131, v130, v131, s[6:7]
	v_fma_f32 v130, -v132, v130, v0
	v_cmp_lt_f32_e64 s[6:7], 0, v130
	s_nop 1
	v_cndmask_b32_e64 v130, v131, v132, s[6:7]
	v_mul_f32_e32 v131, 0x37800000, v130
	v_cndmask_b32_e32 v130, v130, v131, vcc
	v_cmp_class_f32_e32 vcc, v0, v241
	s_nop 1
	v_cndmask_b32_e32 v0, v130, v0, vcc
	v_div_scale_f32 v130, s[6:7], v0, v0, 1.0
	v_rcp_f32_e32 v131, v130
	s_nop 0
	v_fma_f32 v132, -v130, v131, 1.0
	v_fmac_f32_e32 v131, v132, v131
	v_div_scale_f32 v132, vcc, 1.0, v0, 1.0
	v_mul_f32_e32 v133, v132, v131
	v_fma_f32 v134, -v130, v133, v132
	v_fmac_f32_e32 v133, v134, v131
	v_fma_f32 v130, -v130, v133, v132
	v_div_fmas_f32 v130, v130, v131, v133
	v_div_fixup_f32 v0, v130, v0, 1.0
	v_pk_mul_f32 v[130:131], v[38:39], v[0:1] op_sel_hi:[1,0]
	v_pk_mul_f32 v[132:133], v[40:41], v[0:1] op_sel_hi:[1,0]
	v_pk_mul_f32 v[148:149], v[14:15], v[0:1] op_sel_hi:[1,0]
	v_pk_mul_f32 v[150:151], v[16:17], v[0:1] op_sel_hi:[1,0]
	v_pk_mul_f32 v[136:137], v[168:169], v[132:133]
	v_pk_mul_f32 v[134:135], v[170:171], v[130:131]
	v_pk_mul_f32 v[130:131], v[34:35], v[0:1] op_sel_hi:[1,0]
	v_pk_mul_f32 v[132:133], v[36:37], v[0:1] op_sel_hi:[1,0]
	v_pk_mul_f32 v[180:181], v[172:173], v[150:151]
	v_pk_mul_f32 v[182:183], v[174:175], v[148:149]
	v_pk_mul_f32 v[148:149], v[10:11], v[0:1] op_sel_hi:[1,0]
	v_pk_mul_f32 v[150:151], v[12:13], v[0:1] op_sel_hi:[1,0]
	v_pk_mul_f32 v[132:133], v[176:177], v[132:133]
	v_pk_mul_f32 v[130:131], v[178:179], v[130:131]
	v_pk_mul_f32 v[184:185], v[164:165], v[150:151]
	v_pk_mul_f32 v[186:187], v[166:167], v[148:149]
	s_and_b64 vcc, exec, s[4:5]
	s_cbranch_vccnz .LBB0_200
	s_waitcnt vmcnt(0)
	v_pk_mul_f32 v[150:151], v[182:183], v[210:211]
	v_pk_mul_f32 v[148:149], v[180:181], v[212:213]
	v_pk_fma_f32 v[214:215], v[134:135], v[202:203], v[150:151] neg_lo:[0,0,1] neg_hi:[0,0,1]
	v_pk_mul_f32 v[134:135], v[134:135], v[210:211]
	v_pk_fma_f32 v[216:217], v[136:137], v[204:205], v[148:149] neg_lo:[0,0,1] neg_hi:[0,0,1]
	v_pk_mul_f32 v[136:137], v[136:137], v[212:213]
	v_pk_fma_f32 v[182:183], v[182:183], v[202:203], v[134:135]
	v_pk_mul_f32 v[134:135], v[184:185], v[208:209]
	v_pk_mul_f32 v[148:149], v[186:187], v[206:207]
	v_pk_fma_f32 v[180:181], v[180:181], v[204:205], v[136:137]
	v_pk_fma_f32 v[136:137], v[132:133], v[200:201], v[134:135] neg_lo:[0,0,1] neg_hi:[0,0,1]
	v_pk_fma_f32 v[134:135], v[130:131], v[198:199], v[148:149] neg_lo:[0,0,1] neg_hi:[0,0,1]
	v_pk_mul_f32 v[132:133], v[132:133], v[208:209]
	v_pk_mul_f32 v[130:131], v[130:131], v[206:207]
	v_pk_fma_f32 v[184:185], v[184:185], v[200:201], v[132:133]
	v_pk_fma_f32 v[186:187], v[186:187], v[198:199], v[130:131]
	v_mov_b64_e32 v[130:131], v[134:135]
	v_mov_b64_e32 v[132:133], v[136:137]
	v_mov_b64_e32 v[134:135], v[214:215]
	v_mov_b64_e32 v[136:137], v[216:217]
